# P6 four-workgroup exchange poll loop backs off with s_sleep 8 instead of 2 (on top of the group-barrier back-off)
# baseline (speedup 1.0000x reference)
;     __device__ __forceinline__ void fused(f32x4 (&acc)[2][2][4][2], const Unit& u, int wr, int wc, int fr_, int fq_, LAS unsigned char* lds, int wid, int lane_) const {
;     ...
;         if (wid == 0) {
;             bool dead = false; const unsigned long long t0 = __builtin_amdgcn_s_memrealtime(); const unsigned want = 8u * 4u;
;             for (;;) {
;                 if ((unsigned)__builtin_amdgcn_readfirstlane(__hip_atomic_load(cnt + 64 * u.pm, __ATOMIC_RELAXED, __HIP_MEMORY_SCOPE_AGENT)) >= want) break;
;                 if (__builtin_amdgcn_s_memrealtime() - t0 > 2000000ull) { if (lane == 0) __hip_atomic_store(tmo, 1u, __ATOMIC_RELAXED, __HIP_MEMORY_SCOPE_AGENT); dead = true; break; }
;                 __builtin_amdgcn_s_sleep(2);
;             }
;             __builtin_amdgcn_fence(__ATOMIC_ACQUIRE, "agent");
;             if (lane == 0) flag[0] = dead ? 1u : 0u;
;         }
.LBB0_1205:
	global_load_dword v8, v7, s[0:1] sc1
	s_mov_b64 s[12:13], -1
	s_waitcnt vmcnt(0)
	v_readfirstlane_b32 s16, v8
	s_cmp_gt_u32 s16, 31
	s_mov_b64 s[16:17], -1
	s_cbranch_scc1 .LBB0_1204
	s_memrealtime s[12:13]
	s_waitcnt lgkmcnt(0)
	s_sub_u32 s12, s12, s10
	s_subb_u32 s13, s13, s11
	v_cmp_lt_u64_e32 vcc, s[12:13], v[4:5]
	s_cbranch_vccz .LBB0_1203
	s_mov_b64 s[16:17], 0
	s_sleep 8
	s_branch .LBB0_1203
